# placement: F1G loop head at 8 mod 64 (FFN-F2 40, F3 56)
# baseline (speedup 1.0000x reference)
.LBB0_957:
	s_add_u32 s41, s8, 0x13900000
	s_addc_u32 s42, s9, 0
	s_add_u32 s43, s8, 0x2600000
	s_mul_i32 s72, s14, 0xc000
	s_addc_u32 s44, s9, 0
	s_lshl_b64 s[14:15], s[72:73], 2
	s_add_u32 s8, s8, s14
	s_addc_u32 s9, s9, s15
	s_add_u32 s45, s8, 0x58000
	s_addc_u32 s46, s9, 0
	s_lshl_b32 s8, s13, 5
	s_and_b32 s13, s8, 0x60
	s_add_i32 m0, s19, 0x18000
	v_lshl_add_u64 v[6:7], v[6:7], 0, s[74:75]
	s_lshl_b32 s14, s12, 13
	s_lshl_b32 s15, s13, 7
	s_waitcnt vmcnt(2)
	s_barrier
	global_load_lds_dwordx4 v[6:7], off
	v_lshl_add_u64 v[4:5], v[4:5], 0, s[74:75]
	s_add_i32 m0, s19, 0x1a000
	s_add_i32 s47, s19, 0x8000
	s_add_i32 s48, s19, 0xa000
	global_load_lds_dwordx4 v[4:5], off
	v_lshl_add_u64 v[0:1], v[0:1], 0, s[74:75]
	s_mov_b32 m0, s47
	s_add_u32 s8, s30, 0x80080
	global_load_lds_dwordx4 v[0:1], off
	v_lshl_add_u64 v[0:1], v[2:3], 0, s[74:75]
	s_mov_b32 m0, s48
	s_addc_u32 s9, s31, 0
	global_load_lds_dwordx4 v[0:1], off
	s_add_i32 m0, s19, 0x1c000
	v_lshl_add_u64 v[0:1], s[8:9], 0, v[130:131]
	global_load_lds_dwordx4 v[0:1], off
	v_lshl_add_u64 v[0:1], s[8:9], 0, v[134:135]
	s_add_i32 m0, s19, 0x1e000
	s_cmpk_lt_u32 s10, 0x100
	global_load_lds_dwordx4 v[0:1], off
	v_lshrrev_b32_e32 v0, 1, v8
	v_and_b32_e32 v0, 24, v0
	v_and_b32_e32 v1, 15, v8
	v_lshlrev_b32_e32 v2, 1, v0
	v_lshl_or_b32 v136, s12, 6, v1
	v_lshl_or_b32 v1, v1, 6, v2
	v_lshlrev_b32_e32 v2, 2, v8
	v_and_b32_e32 v2, 32, v2
	v_bitop3_b32 v3, v1, s14, v2 bitop3:0xde
	v_bitop3_b32 v143, v1, s15, v2 bitop3:0xde
	v_lshlrev_b32_e32 v1, 15, v9
	v_and_b32_e32 v1, 0xffff0000, v1
	v_lshl_add_u32 v1, v10, 12, v1
	v_and_b32_e32 v2, 1, v9
	v_lshl_or_b32 v1, v2, 6, v1
	v_lshl_add_u32 v138, v11, 1, v1
	v_lshlrev_b32_e32 v1, 15, v12
	v_and_b32_e32 v1, 0xffff0000, v1
	s_waitcnt vmcnt(6)
	v_lshl_add_u32 v1, v13, 12, v1
	v_and_b32_e32 v2, 1, v12
	v_lshl_or_b32 v1, v2, 6, v1
	s_cselect_b64 s[8:9], -1, 0
	v_ashrrev_i32_e32 v137, 31, v136
	v_mov_b32_e32 v139, v177
	v_lshl_add_u32 v140, v14, 1, v1
	v_mov_b32_e32 v141, v177
	s_mov_b32 s49, 0
	v_add_u32_e32 v147, 0, v3
	s_lshl_b32 s10, s13, 1
	v_lshlrev_b32_e32 v176, 1, v0
	s_barrier
	s_branch .LBB0_960
	s_nop 0
	s_nop 0
	s_nop 0
	s_nop 0

.LBB0_1051:
	v_lshrrev_b32_e32 v15, 1, v14
	v_and_b32_e32 v15, 24, v15
	v_and_b32_e32 v221, 15, v14
	v_lshlrev_b32_e32 v16, 1, v15
	v_lshlrev_b32_e32 v14, 2, v14
	s_lshl_b32 s3, s3, 5
	s_lshl_b32 s60, s4, 6
	v_lshl_or_b32 v16, v221, 6, v16
	s_lshl_b32 s4, s4, 13
	v_and_b32_e32 v14, 32, v14
	s_and_b32 s3, s3, 0x60
	s_add_i32 m0, s42, 0x18000
	v_lshl_add_u64 v[6:7], v[6:7], 0, s[74:75]
	v_bitop3_b32 v17, v16, s4, v14 bitop3:0xde
	s_lshl_b32 s4, s3, 7
	s_waitcnt vmcnt(2)
	s_barrier
	global_load_lds_dwordx4 v[6:7], off
	v_lshl_add_u64 v[4:5], v[4:5], 0, s[74:75]
	s_add_i32 m0, s42, 0x1a000
	s_add_i32 s61, s42, 0x8000
	s_add_i32 s64, s42, 0xa000
	v_bitop3_b32 v222, v16, s4, v14 bitop3:0xde
	global_load_lds_dwordx4 v[4:5], off
	v_lshl_add_u64 v[0:1], v[0:1], 0, s[74:75]
	s_mov_b32 m0, s61
	s_add_u32 s4, s12, 0x80080
	global_load_lds_dwordx4 v[0:1], off
	v_lshl_add_u64 v[0:1], v[2:3], 0, s[74:75]
	s_mov_b32 m0, s64
	s_addc_u32 s5, s13, 0
	global_load_lds_dwordx4 v[0:1], off
	s_add_i32 m0, s42, 0x1c000
	v_lshl_add_u64 v[0:1], s[4:5], 0, v[176:177]
	global_load_lds_dwordx4 v[0:1], off
	v_lshl_add_u64 v[0:1], s[4:5], 0, v[178:179]
	s_add_i32 m0, s42, 0x1e000
	s_cmpk_lt_u32 s2, 0x100
	global_load_lds_dwordx4 v[0:1], off
	v_lshlrev_b32_e32 v0, 15, v12
	v_and_b32_e32 v0, 0xffff0000, v0
	v_lshl_add_u32 v0, v11, 12, v0
	v_and_b32_e32 v1, 1, v12
	v_lshl_or_b32 v0, v1, 6, v0
	v_lshl_add_u32 v184, v13, 1, v0
	v_lshlrev_b32_e32 v0, 15, v8
	s_cselect_b64 s[40:41], -1, 0
	s_add_u32 s46, s18, 0x5800
	v_and_b32_e32 v0, 0xffff0000, v0
	s_waitcnt vmcnt(6)
	s_addc_u32 s47, s19, 0
	v_lshl_add_u32 v0, v9, 12, v0
	v_and_b32_e32 v1, 1, v8
	s_add_u32 s48, s18, 0xb000
	v_lshl_or_b32 v0, v1, 6, v0
	v_readlane_b32 s14, v254, 39
	s_mov_b32 s65, 0
	v_cmp_eq_u32_e64 s[4:5], 0, v221
	v_cmp_eq_u32_e64 s[6:7], 15, v221
	s_addc_u32 s49, s19, 0
	v_or_b32_e32 v223, s3, v15
	v_mov_b32_e32 v185, v177
	v_lshl_add_u32 v186, v10, 1, v0
	v_mov_b32_e32 v187, v177
	v_add_u32_e32 v224, 0, v17
	v_readlane_b32 s2, v254, 38
	s_mov_b32 s3, s14
	s_barrier
	v_readlane_b32 s15, v254, 40
	s_branch .LBB0_1054
	s_nop 0
	s_nop 0
	s_nop 0
	s_nop 0
	s_nop 0
	s_nop 0
	s_nop 0
	s_nop 0
	s_nop 0
	s_nop 0
	s_nop 0
	s_nop 0
